# prologue x->bf16 and p->bf16 loops: 8 loads in flight per wave instead of a serialized load-wait-store per 1 KB
# speedup vs baseline: 1.0036x; 1.0036x over previous
.LBB0_63:
	v_add_co_u32_e32 v24, vcc, 0xfffff000, v6
	v_lshl_add_u64 v[20:21], s[8:9], 0, v[4:5]
	s_nop 0
	v_addc_co_u32_e32 v25, vcc, -1, v7, vcc
	v_add_co_u32_e32 v48, vcc, s11, v20
	s_waitcnt lgkmcnt(0)
	s_nop 0
	v_addc_co_u32_e32 v49, vcc, 0, v21, vcc
	global_load_dwordx4 v[16:19], v[24:25], off offset:-3072
	global_load_dwordx4 v[20:23], v[24:25], off offset:-2048
	global_load_dwordx4 v[24:27], v[24:25], off offset:-1024
	global_load_dwordx4 v[28:31], v[6:7], off offset:-4096
	global_load_dwordx4 v[32:35], v[6:7], off offset:-3072
	global_load_dwordx4 v[36:39], v[6:7], off offset:-2048
	global_load_dwordx4 v[40:43], v[6:7], off offset:-1024
	global_load_dwordx4 v[44:47], v[6:7], off
	s_waitcnt vmcnt(7)
	v_cvt_pk_bf16_f32 v100, v16, v17
	v_cvt_pk_bf16_f32 v101, v18, v19
	global_store_dwordx2 v[48:49], v[100:101], off
	s_waitcnt vmcnt(7)
	v_cvt_pk_bf16_f32 v102, v20, v21
	v_cvt_pk_bf16_f32 v103, v22, v23
	global_store_dwordx2 v[48:49], v[102:103], off offset:512
	s_waitcnt vmcnt(7)
	v_cvt_pk_bf16_f32 v104, v24, v25
	v_cvt_pk_bf16_f32 v105, v26, v27
	global_store_dwordx2 v[48:49], v[104:105], off offset:1024
	s_waitcnt vmcnt(7)
	v_cvt_pk_bf16_f32 v106, v28, v29
	v_cvt_pk_bf16_f32 v107, v30, v31
	global_store_dwordx2 v[48:49], v[106:107], off offset:1536
	s_waitcnt vmcnt(7)
	v_cvt_pk_bf16_f32 v108, v32, v33
	v_cvt_pk_bf16_f32 v109, v34, v35
	global_store_dwordx2 v[48:49], v[108:109], off offset:2048
	s_waitcnt vmcnt(7)
	v_cvt_pk_bf16_f32 v110, v36, v37
	v_cvt_pk_bf16_f32 v111, v38, v39
	global_store_dwordx2 v[48:49], v[110:111], off offset:2560
	s_waitcnt vmcnt(7)
	v_cvt_pk_bf16_f32 v112, v40, v41
	v_cvt_pk_bf16_f32 v113, v42, v43
	global_store_dwordx2 v[48:49], v[112:113], off offset:3072
	v_cmp_lt_i32_e32 vcc, v10, v9
	v_mul_f32_e32 v17, v17, v17
	v_mul_f32_e32 v19, v19, v19
	v_fmac_f32_e32 v17, v16, v16
	v_fmac_f32_e32 v19, v18, v18
	v_add_f32_e32 v16, v17, v19
	v_cndmask_b32_e32 v50, v8, v10, vcc
	v_mul_f32_e32 v17, v21, v21
	v_mul_f32_e32 v18, v23, v23
	v_fmac_f32_e32 v17, v20, v20
	v_fmac_f32_e32 v18, v22, v22
	v_add_f32_e32 v17, v17, v18
	v_add_f32_e32 v16, v16, v17
	v_mul_f32_e32 v17, v25, v25
	v_mul_f32_e32 v18, v27, v27
	v_fmac_f32_e32 v17, v24, v24
	v_fmac_f32_e32 v18, v26, v26
	v_add_f32_e32 v17, v17, v18
	v_add_f32_e32 v16, v16, v17
	v_mul_f32_e32 v17, v29, v29
	v_mul_f32_e32 v18, v31, v31
	v_fmac_f32_e32 v17, v28, v28
	v_fmac_f32_e32 v18, v30, v30
	v_add_f32_e32 v17, v17, v18
	v_add_f32_e32 v16, v16, v17
	v_mul_f32_e32 v17, v33, v33
	v_mul_f32_e32 v18, v35, v35
	v_fmac_f32_e32 v17, v32, v32
	v_fmac_f32_e32 v18, v34, v34
	v_add_f32_e32 v17, v17, v18
	v_add_f32_e32 v16, v16, v17
	v_mul_f32_e32 v17, v37, v37
	v_mul_f32_e32 v18, v39, v39
	v_fmac_f32_e32 v17, v36, v36
	v_fmac_f32_e32 v18, v38, v38
	v_add_f32_e32 v17, v17, v18
	v_add_f32_e32 v16, v16, v17
	v_mul_f32_e32 v17, v41, v41
	v_mul_f32_e32 v18, v43, v43
	v_fmac_f32_e32 v17, v40, v40
	v_fmac_f32_e32 v18, v42, v42
	v_add_f32_e32 v17, v17, v18
	v_add_f32_e32 v16, v16, v17
	s_waitcnt vmcnt(7)
	v_mul_f32_e32 v17, v45, v45
	v_mul_f32_e32 v18, v47, v47
	v_fmac_f32_e32 v17, v44, v44
	v_fmac_f32_e32 v18, v46, v46
	v_add_f32_e32 v17, v17, v18
	v_lshlrev_b32_e32 v50, 2, v50
	v_add_f32_e32 v16, v16, v17
	ds_bpermute_b32 v17, v50, v16
	v_cmp_lt_i32_e32 vcc, v11, v9
	s_waitcnt lgkmcnt(0)
	v_add_f32_e32 v16, v16, v17
	v_cndmask_b32_e32 v18, v8, v11, vcc
	v_lshlrev_b32_e32 v18, 2, v18
	ds_bpermute_b32 v17, v18, v16
	v_cmp_lt_i32_e32 vcc, v12, v9
	s_waitcnt lgkmcnt(0)
	v_add_f32_e32 v16, v16, v17
	v_cndmask_b32_e32 v18, v8, v12, vcc
	v_lshlrev_b32_e32 v18, 2, v18
	ds_bpermute_b32 v17, v18, v16
	v_cmp_lt_i32_e32 vcc, v13, v9
	s_waitcnt lgkmcnt(0)
	v_add_f32_e32 v16, v16, v17
	v_cndmask_b32_e32 v18, v8, v13, vcc
	v_lshlrev_b32_e32 v18, 2, v18
	ds_bpermute_b32 v17, v18, v16
	v_cmp_lt_i32_e32 vcc, v14, v9
	s_waitcnt lgkmcnt(0)
	v_add_f32_e32 v16, v16, v17
	v_cndmask_b32_e32 v18, v8, v14, vcc
	v_lshlrev_b32_e32 v18, 2, v18
	ds_bpermute_b32 v17, v18, v16
	v_cmp_lt_i32_e32 vcc, v15, v9
	s_waitcnt lgkmcnt(0)
	v_add_f32_e32 v16, v16, v17
	v_cndmask_b32_e32 v18, v8, v15, vcc
	v_lshlrev_b32_e32 v17, 2, v18
	ds_bpermute_b32 v17, v17, v16
	v_cvt_pk_bf16_f32 v18, v44, v45
	v_cvt_pk_bf16_f32 v19, v46, v47
	global_store_dwordx2 v[48:49], v[18:19], off offset:3584
	s_and_saveexec_b64 s[20:21], s[4:5]
	s_cbranch_execz .LBB0_62
	s_waitcnt lgkmcnt(0)
	v_add_f32_e32 v16, v16, v17
	v_cndmask_b32_e64 v18, 0, v16, s[6:7]
	v_lshl_add_u64 v[16:17], s[8:9], 0, v[2:3]
	global_store_dword v[16:17], v18, off
	s_branch .LBB0_62
.LBB0_65:
	v_lshl_add_u32 v2, s2, 9, v69
	s_mov_b32 s4, 0x100000
	s_mov_b64 s[6:7], s[0:1]
	v_cmp_gt_i32_e32 vcc, s4, v2
	s_and_saveexec_b64 s[4:5], vcc
	s_cbranch_execz .LBB0_68
	s_load_dwordx2 s[6:7], s[6:7], 0x8
	s_waitcnt lgkmcnt(0)
	s_add_u32 s10, s8, 0x800000
	s_addc_u32 s11, s9, 0
	s_lshl_b32 s14, s42, 9
	s_mov_b64 s[12:13], 0
	s_mov_b32 s15, 0xfffff
	v_mov_b32_e32 v4, v2
	s_cmp_lg_u32 s42, 0x100
	s_cbranch_scc1 .LBB0_67
	v_lshlrev_b32_e32 v132, 4, v4
	v_lshlrev_b32_e32 v133, 3, v4
	global_load_dwordx4 v[100:103], v132, s[6:7]
	v_add_u32_e32 v134, 0x200000, v132
	global_load_dwordx4 v[104:107], v134, s[6:7]
	v_add_u32_e32 v134, 0x400000, v132
	global_load_dwordx4 v[108:111], v134, s[6:7]
	v_add_u32_e32 v134, 0x600000, v132
	global_load_dwordx4 v[112:115], v134, s[6:7]
	v_add_u32_e32 v134, 0x800000, v132
	global_load_dwordx4 v[116:119], v134, s[6:7]
	v_add_u32_e32 v134, 0xa00000, v132
	global_load_dwordx4 v[120:123], v134, s[6:7]
	v_add_u32_e32 v134, 0xc00000, v132
	global_load_dwordx4 v[124:127], v134, s[6:7]
	v_add_u32_e32 v134, 0xe00000, v132
	global_load_dwordx4 v[128:131], v134, s[6:7]
	s_waitcnt vmcnt(7)
	v_cvt_pk_bf16_f32 v136, v100, v101
	v_cvt_pk_bf16_f32 v137, v102, v103
	global_store_dwordx2 v133, v[136:137], s[10:11]
	s_waitcnt vmcnt(7)
	v_cvt_pk_bf16_f32 v138, v104, v105
	v_cvt_pk_bf16_f32 v139, v106, v107
	v_add_u32_e32 v135, 0x100000, v133
	global_store_dwordx2 v135, v[138:139], s[10:11]
	s_waitcnt vmcnt(7)
	v_cvt_pk_bf16_f32 v140, v108, v109
	v_cvt_pk_bf16_f32 v141, v110, v111
	v_add_u32_e32 v135, 0x200000, v133
	global_store_dwordx2 v135, v[140:141], s[10:11]
	s_waitcnt vmcnt(7)
	v_cvt_pk_bf16_f32 v142, v112, v113
	v_cvt_pk_bf16_f32 v143, v114, v115
	v_add_u32_e32 v135, 0x300000, v133
	global_store_dwordx2 v135, v[142:143], s[10:11]
	s_waitcnt vmcnt(7)
	v_cvt_pk_bf16_f32 v144, v116, v117
	v_cvt_pk_bf16_f32 v145, v118, v119
	v_add_u32_e32 v135, 0x400000, v133
	global_store_dwordx2 v135, v[144:145], s[10:11]
	s_waitcnt vmcnt(7)
	v_cvt_pk_bf16_f32 v146, v120, v121
	v_cvt_pk_bf16_f32 v147, v122, v123
	v_add_u32_e32 v135, 0x500000, v133
	global_store_dwordx2 v135, v[146:147], s[10:11]
	s_waitcnt vmcnt(7)
	v_cvt_pk_bf16_f32 v148, v124, v125
	v_cvt_pk_bf16_f32 v149, v126, v127
	v_add_u32_e32 v135, 0x600000, v133
	global_store_dwordx2 v135, v[148:149], s[10:11]
	s_waitcnt vmcnt(7)
	v_cvt_pk_bf16_f32 v150, v128, v129
	v_cvt_pk_bf16_f32 v151, v130, v131
	v_add_u32_e32 v135, 0x700000, v133
	global_store_dwordx2 v135, v[150:151], s[10:11]
	s_branch .LBB0_68
